# blocked H layout + per-XCD column-tile rotation in P4
# baseline (speedup 1.0000x reference)
;     __host__ __device__ bool next(int i, Unit& u) const {
;     ...
;         int wgid = (int)L; { const int q = nwg / NXCD, r = nwg % NXCD, xcd = wgid % NXCD, off = wgid / NXCD; wgid = (xcd < r ? xcd * (q + 1) : r * (q + 1) + (xcd - r) * q) + off; }
;         const int nig = WGM * nN, gid = wgid / nig, fm = gid * WGM, gsz = (nM - fm) < WGM ? (nM - fm) : WGM;
;         u.pm = fm + ((wgid % nig) % gsz); u.pn = (wgid % nig) / gsz; u.idx = i; return true;
.LBB0_1367:
	s_or_b64 exec, exec, s[6:7]
	s_cmp_gt_i32 s30, 0
	s_cselect_b64 s[0:1], -1, 0
	s_cmpk_lt_i32 s2, 0xc00
	s_cselect_b64 s[4:5], -1, 0
	s_and_b64 s[0:1], s[4:5], s[0:1]
	v_cndmask_b32_e64 v1, 0, 1, s[0:1]
	v_cmp_ne_u32_e64 s[4:5], 1, v1
	s_andn2_b64 vcc, exec, s[0:1]
	v_readfirstlane_b32 s12, v208
	s_waitcnt lgkmcnt(0)
	s_barrier
	s_cbranch_vccnz .LBB0_1370
	s_lshr_b32 s0, s3, 29
	s_add_i32 s0, s2, s0
	s_ashr_i32 s1, s0, 3
	s_and_b32 s0, s0, -8
	s_sub_i32 s0, s2, s0
	s_cmp_lt_i32 s0, 0
	s_movk_i32 s6, 0x181
	s_cselect_b32 s6, s6, 0x180
	s_mul_i32 s0, s0, s6
	s_add_i32 s0, s0, s1
	s_ashr_i32 s1, s0, 31
	s_lshr_b32 s1, s1, 25
	s_add_i32 s1, s0, s1
	s_ashr_i32 s6, s1, 7
	s_and_b32 s1, s1, 0xff80
	s_sub_i32 s0, s0, s1
	s_bfe_i32 s1, s0, 0x80000
	s_bfe_u32 s1, s1, 0x3000c
	s_add_i32 s1, s0, s1
	s_and_b32 s7, s1, 0xf8
	s_sub_i32 s0, s0, s7
	s_lshl_b32 s6, s6, 3
	s_sext_i32_i8 s0, s0
	s_add_i32 s24, s6, s0
	s_bfe_i32 s0, s1, 0x80000
	s_sext_i32_i16 s0, s0
	s_ashr_i32 s22, s0, 3
	s_and_b32 s98, s2, 7
	s_lshl_b32 s98, s98, 2
	s_add_i32 s22, s22, s98
	s_and_b32 s22, s22, 15
	s_and_b64 vcc, exec, s[4:5]
	s_cbranch_vccz .LBB0_1371
